# NORM bias GEMV: next weight row prefetched under the current row's reductions
# speedup vs baseline: 1.0880x; 1.0062x over previous
.LBB0_176:
	s_or_b64 exec, exec, s[48:49]
	s_waitcnt lgkmcnt(0)
	s_setprio 0
	s_barrier
	ds_read_b128 v[2:5], v145
	ds_read_b128 v[6:9], v145 offset:16
	ds_read_b128 v[10:13], v145 offset:32
	ds_read_b128 v[14:17], v145 offset:48
	s_waitcnt vmcnt(4)
	ds_read_b128 v[18:21], v145 offset:4096
	ds_read_b128 v[22:25], v145 offset:4112
	ds_read_b128 v[26:29], v145 offset:4128
	ds_read_b128 v[30:33], v145 offset:4144
	ds_read_b128 v[34:37], v145 offset:8192
	ds_read_b128 v[38:41], v145 offset:8208
	ds_read_b128 v[42:45], v145 offset:8224
	ds_read_b128 v[46:49], v145 offset:8240
	ds_read_b128 v[50:53], v145 offset:12288
	ds_read_b128 v[54:57], v145 offset:12304
	ds_read_b128 v[58:61], v145 offset:12320
	ds_read_b128 v[62:65], v145 offset:12336
	ds_read_b128 v[66:69], v145 offset:16384
	ds_read_b128 v[70:73], v145 offset:16400
	ds_read_b128 v[74:77], v145 offset:16416
	ds_read_b128 v[78:81], v145 offset:16432
	ds_read_b128 v[82:85], v145 offset:20480
	ds_read_b128 v[86:89], v145 offset:20496
	ds_read_b128 v[90:93], v145 offset:20512
	ds_read_b128 v[94:97], v145 offset:20528
	ds_read_b128 v[98:101], v145 offset:24576
	ds_read_b128 v[102:105], v145 offset:24592
	ds_read_b128 v[106:109], v145 offset:24608
	ds_read_b128 v[110:113], v145 offset:24624
	ds_read_b128 v[114:117], v145 offset:28672
	ds_read_b128 v[118:121], v145 offset:28688
	ds_read_b128 v[122:125], v145 offset:28704
	ds_read_b128 v[126:129], v145 offset:28720
	v_lshl_add_u32 v138, s7, 5, v144
	s_mov_b32 s3, s77
	s_lshl_b64 s[2:3], s[2:3], 17
	v_ashrrev_i32_e32 v139, 31, v138
	v_lshl_add_u64 v[136:137], v[138:139], 2, s[2:3]
	v_lshl_add_u64 v[140:141], v[132:133], 0, s[22:23]
	v_lshlrev_b64 v[138:139], 11, v[138:139]
	v_lshl_add_u64 v[138:139], v[140:141], 0, v[138:139]
	v_lshl_add_u64 v[138:139], s[76:77], 1, v[138:139]
	s_mov_b32 s7, 8
	v_lshl_add_u64 v[244:245], s[18:19], 0, v[138:139]
	global_load_dwordx4 v[198:201], v[244:245], off offset:16
	global_load_dwordx4 v[202:205], v[244:245], off
	s_waitcnt vmcnt(0)
	s_branch .LBB0_178

.LBB0_178:
	s_waitcnt vmcnt(8)
	v_lshlrev_b32_e32 v0, 16, v198
	s_nop 0
	v_and_b32_e32 v169, 0xffff0000, v202
	v_lshlrev_b32_e32 v163, 16, v202
	v_and_b32_e32 v161, 0xffff0000, v198
	v_and_b32_e32 v170, 0xffff0000, v204
	s_waitcnt lgkmcnt(14)
	v_mul_f32_e32 v140, v3, v169
	v_lshlrev_b32_e32 v167, 16, v203
	v_lshlrev_b32_e32 v164, 16, v204
	v_fmac_f32_e32 v140, v2, v163
	v_mul_f32_e32 v141, v7, v170
	v_and_b32_e32 v165, 0xffff0000, v203
	v_lshlrev_b32_e32 v168, 16, v205
	v_fmac_f32_e32 v140, v4, v167
	v_fmac_f32_e32 v141, v6, v164
	v_and_b32_e32 v166, 0xffff0000, v205
	v_fmac_f32_e32 v140, v5, v165
	v_fmac_f32_e32 v141, v8, v168
	v_add_f32_e32 v140, 0, v140
	v_fmac_f32_e32 v141, v9, v166
	v_add_f32_e32 v140, v141, v140
	v_mul_f32_e32 v141, v11, v161
	v_lshlrev_b32_e32 v159, 16, v199
	v_fmac_f32_e32 v141, v10, v0
	v_and_b32_e32 v157, 0xffff0000, v199
	v_fmac_f32_e32 v141, v12, v159
	v_and_b32_e32 v162, 0xffff0000, v200
	v_fmac_f32_e32 v141, v13, v157
	s_waitcnt lgkmcnt(0)
	v_lshlrev_b32_e32 v156, 16, v200
	v_add_f32_e32 v140, v141, v140
	v_mul_f32_e32 v141, v15, v162
	v_lshlrev_b32_e32 v160, 16, v201
	v_fmac_f32_e32 v141, v14, v156
	v_and_b32_e32 v158, 0xffff0000, v201
	v_lshl_add_u64 v[244:245], v[244:245], 0, s[24:25]
	global_load_dwordx4 v[198:201], v[244:245], off offset:16
	global_load_dwordx4 v[202:205], v[244:245], off
	v_fmac_f32_e32 v141, v16, v160
	v_fmac_f32_e32 v141, v17, v158
	v_add_f32_e32 v180, v141, v140
	v_mul_f32_e32 v171, v19, v169
	v_fmac_f32_e32 v171, v18, v163
	s_waitcnt lgkmcnt(0)
	v_mul_f32_e32 v172, v23, v170
	v_fmac_f32_e32 v171, v20, v167
	v_fmac_f32_e32 v172, v22, v164
	v_fmac_f32_e32 v171, v21, v165
	v_fmac_f32_e32 v172, v24, v168
	v_add_f32_e32 v171, 0, v171
	v_fmac_f32_e32 v172, v25, v166
	v_add_f32_e32 v171, v172, v171
	v_mul_f32_e32 v172, v27, v161
	v_fmac_f32_e32 v172, v26, v0
	v_fmac_f32_e32 v172, v28, v159
	v_fmac_f32_e32 v172, v29, v157
	v_add_f32_e32 v171, v172, v171
	v_mul_f32_e32 v172, v31, v162
	v_fmac_f32_e32 v172, v30, v156
	v_fmac_f32_e32 v172, v32, v160
	v_fmac_f32_e32 v172, v33, v158
	v_add_f32_e32 v181, v172, v171
	v_mul_f32_e32 v171, v35, v169
	v_fmac_f32_e32 v171, v34, v163
	s_waitcnt lgkmcnt(0)
	v_mul_f32_e32 v172, v39, v170
	v_fmac_f32_e32 v171, v36, v167
	v_fmac_f32_e32 v172, v38, v164
	v_fmac_f32_e32 v171, v37, v165
	v_fmac_f32_e32 v172, v40, v168
	v_add_f32_e32 v171, 0, v171
	v_fmac_f32_e32 v172, v41, v166
	v_add_f32_e32 v171, v172, v171
	v_mul_f32_e32 v172, v43, v161
	v_fmac_f32_e32 v172, v42, v0
	v_fmac_f32_e32 v172, v44, v159
	v_fmac_f32_e32 v172, v45, v157
	v_add_f32_e32 v171, v172, v171
	v_mul_f32_e32 v172, v47, v162
	v_fmac_f32_e32 v172, v46, v156
	v_fmac_f32_e32 v172, v48, v160
	v_fmac_f32_e32 v172, v49, v158
	v_add_f32_e32 v182, v172, v171
	v_mul_f32_e32 v171, v51, v169
	v_fmac_f32_e32 v171, v50, v163
	s_waitcnt lgkmcnt(0)
	v_mul_f32_e32 v172, v55, v170
	v_fmac_f32_e32 v171, v52, v167
	v_fmac_f32_e32 v172, v54, v164
	v_fmac_f32_e32 v171, v53, v165
	v_fmac_f32_e32 v172, v56, v168
	v_add_f32_e32 v171, 0, v171
	v_fmac_f32_e32 v172, v57, v166
	v_add_f32_e32 v171, v172, v171
	v_mul_f32_e32 v172, v59, v161
	v_fmac_f32_e32 v172, v58, v0
	v_fmac_f32_e32 v172, v60, v159
	v_fmac_f32_e32 v172, v61, v157
	v_add_f32_e32 v171, v172, v171
	v_mul_f32_e32 v172, v63, v162
	v_fmac_f32_e32 v172, v62, v156
	v_fmac_f32_e32 v172, v64, v160
	v_fmac_f32_e32 v172, v65, v158
	v_add_f32_e32 v183, v172, v171
	v_mul_f32_e32 v171, v67, v169
	v_fmac_f32_e32 v171, v66, v163
	s_waitcnt lgkmcnt(0)
	v_mul_f32_e32 v172, v71, v170
	v_fmac_f32_e32 v171, v68, v167
	v_fmac_f32_e32 v172, v70, v164
	v_fmac_f32_e32 v171, v69, v165
	v_fmac_f32_e32 v172, v72, v168
	v_add_f32_e32 v171, 0, v171
	v_fmac_f32_e32 v172, v73, v166
	v_add_f32_e32 v171, v172, v171
	v_mul_f32_e32 v172, v75, v161
	v_fmac_f32_e32 v172, v74, v0
	v_fmac_f32_e32 v172, v76, v159
	v_fmac_f32_e32 v172, v77, v157
	v_add_f32_e32 v171, v172, v171
	v_mul_f32_e32 v172, v79, v162
	v_fmac_f32_e32 v172, v78, v156
	v_fmac_f32_e32 v172, v80, v160
	v_fmac_f32_e32 v172, v81, v158
	v_add_f32_e32 v184, v172, v171
	v_mul_f32_e32 v171, v83, v169
	v_fmac_f32_e32 v171, v82, v163
	s_waitcnt lgkmcnt(0)
	v_mul_f32_e32 v172, v87, v170
	v_fmac_f32_e32 v171, v84, v167
	v_fmac_f32_e32 v172, v86, v164
	v_fmac_f32_e32 v171, v85, v165
	v_fmac_f32_e32 v172, v88, v168
	v_add_f32_e32 v171, 0, v171
	v_fmac_f32_e32 v172, v89, v166
	v_add_f32_e32 v171, v172, v171
	v_mul_f32_e32 v172, v91, v161
	v_fmac_f32_e32 v172, v90, v0
	v_fmac_f32_e32 v172, v92, v159
	v_fmac_f32_e32 v172, v93, v157
	v_add_f32_e32 v171, v172, v171
	v_mul_f32_e32 v172, v95, v162
	v_fmac_f32_e32 v172, v94, v156
	v_fmac_f32_e32 v172, v96, v160
	v_fmac_f32_e32 v172, v97, v158
	v_add_f32_e32 v185, v172, v171
	v_mul_f32_e32 v171, v99, v169
	v_fmac_f32_e32 v171, v98, v163
	s_waitcnt lgkmcnt(0)
	v_mul_f32_e32 v172, v103, v170
	v_fmac_f32_e32 v171, v100, v167
	v_fmac_f32_e32 v172, v102, v164
	v_fmac_f32_e32 v171, v101, v165
	v_fmac_f32_e32 v172, v104, v168
	v_add_f32_e32 v171, 0, v171
	v_fmac_f32_e32 v172, v105, v166
	v_add_f32_e32 v171, v172, v171
	v_mul_f32_e32 v172, v107, v161
	v_fmac_f32_e32 v172, v106, v0
	v_fmac_f32_e32 v172, v108, v159
	v_fmac_f32_e32 v172, v109, v157
	v_add_f32_e32 v171, v172, v171
	v_mul_f32_e32 v172, v111, v162
	v_fmac_f32_e32 v172, v110, v156
	v_fmac_f32_e32 v172, v112, v160
	v_fmac_f32_e32 v172, v113, v158
	v_add_f32_e32 v186, v172, v171
	v_mul_f32_e32 v169, v115, v169
	v_fmac_f32_e32 v169, v114, v163
	v_fmac_f32_e32 v169, v116, v167
	v_mul_f32_e32 v161, v123, v161
	v_fmac_f32_e32 v169, v117, v165
	v_mul_f32_e32 v165, v119, v170
	v_fmac_f32_e32 v161, v122, v0
	v_fmac_f32_e32 v165, v118, v164
	v_fmac_f32_e32 v161, v124, v159
	v_fmac_f32_e32 v165, v120, v168
	v_fmac_f32_e32 v161, v125, v157
	v_mul_f32_e32 v157, v127, v162
	v_add_f32_e32 v163, 0, v169
	v_fmac_f32_e32 v165, v121, v166
	v_fmac_f32_e32 v157, v126, v156
	v_add_f32_e32 v163, v165, v163
	v_fmac_f32_e32 v157, v128, v160
	v_add_f32_e32 v0, v161, v163
	v_fmac_f32_e32 v157, v129, v158
	v_add_f32_e32 v187, v157, v0
	ds_bpermute_b32 v188, v146, v180
	ds_bpermute_b32 v189, v146, v181
	ds_bpermute_b32 v190, v146, v182
	ds_bpermute_b32 v191, v146, v183
	ds_bpermute_b32 v192, v146, v184
	ds_bpermute_b32 v193, v146, v185
	ds_bpermute_b32 v194, v146, v186
	ds_bpermute_b32 v195, v146, v187
	s_waitcnt lgkmcnt(0)
	v_add_f32_e32 v180, v180, v188
	v_add_f32_e32 v181, v181, v189
	v_add_f32_e32 v182, v182, v190
	v_add_f32_e32 v183, v183, v191
	v_add_f32_e32 v184, v184, v192
	v_add_f32_e32 v185, v185, v193
	v_add_f32_e32 v186, v186, v194
	v_add_f32_e32 v187, v187, v195
	ds_bpermute_b32 v188, v147, v180
	ds_bpermute_b32 v189, v147, v181
	ds_bpermute_b32 v190, v147, v182
	ds_bpermute_b32 v191, v147, v183
	ds_bpermute_b32 v192, v147, v184
	ds_bpermute_b32 v193, v147, v185
	ds_bpermute_b32 v194, v147, v186
	ds_bpermute_b32 v195, v147, v187
	s_waitcnt lgkmcnt(0)
	v_add_f32_e32 v180, v180, v188
	v_add_f32_e32 v181, v181, v189
	v_add_f32_e32 v182, v182, v190
	v_add_f32_e32 v183, v183, v191
	v_add_f32_e32 v184, v184, v192
	v_add_f32_e32 v185, v185, v193
	v_add_f32_e32 v186, v186, v194
	v_add_f32_e32 v187, v187, v195
	ds_bpermute_b32 v188, v148, v180
	ds_bpermute_b32 v189, v148, v181
	ds_bpermute_b32 v190, v148, v182
	ds_bpermute_b32 v191, v148, v183
	ds_bpermute_b32 v192, v148, v184
	ds_bpermute_b32 v193, v148, v185
	ds_bpermute_b32 v194, v148, v186
	ds_bpermute_b32 v195, v148, v187
	s_waitcnt lgkmcnt(0)
	v_add_f32_e32 v180, v180, v188
	v_add_f32_e32 v181, v181, v189
	v_add_f32_e32 v182, v182, v190
	v_add_f32_e32 v183, v183, v191
	v_add_f32_e32 v184, v184, v192
	v_add_f32_e32 v185, v185, v193
	v_add_f32_e32 v186, v186, v194
	v_add_f32_e32 v187, v187, v195
	ds_bpermute_b32 v188, v149, v180
	ds_bpermute_b32 v189, v149, v181
	ds_bpermute_b32 v190, v149, v182
	ds_bpermute_b32 v191, v149, v183
	ds_bpermute_b32 v192, v149, v184
	ds_bpermute_b32 v193, v149, v185
	ds_bpermute_b32 v194, v149, v186
	ds_bpermute_b32 v195, v149, v187
	s_waitcnt lgkmcnt(0)
	v_add_f32_e32 v180, v180, v188
	v_add_f32_e32 v181, v181, v189
	v_add_f32_e32 v182, v182, v190
	v_add_f32_e32 v183, v183, v191
	v_add_f32_e32 v184, v184, v192
	v_add_f32_e32 v185, v185, v193
	v_add_f32_e32 v186, v186, v194
	v_add_f32_e32 v187, v187, v195
	ds_bpermute_b32 v188, v150, v180
	ds_bpermute_b32 v189, v150, v181
	ds_bpermute_b32 v190, v150, v182
	ds_bpermute_b32 v191, v150, v183
	ds_bpermute_b32 v192, v150, v184
	ds_bpermute_b32 v193, v150, v185
	ds_bpermute_b32 v194, v150, v186
	ds_bpermute_b32 v195, v150, v187
	s_waitcnt lgkmcnt(0)
	v_add_f32_e32 v180, v180, v188
	v_add_f32_e32 v181, v181, v189
	v_add_f32_e32 v182, v182, v190
	v_add_f32_e32 v183, v183, v191
	v_add_f32_e32 v184, v184, v192
	v_add_f32_e32 v185, v185, v193
	v_add_f32_e32 v186, v186, v194
	v_add_f32_e32 v187, v187, v195
	ds_bpermute_b32 v188, v151, v180
	ds_bpermute_b32 v189, v151, v181
	ds_bpermute_b32 v190, v151, v182
	ds_bpermute_b32 v191, v151, v183
	ds_bpermute_b32 v192, v151, v184
	ds_bpermute_b32 v193, v151, v185
	ds_bpermute_b32 v194, v151, v186
	ds_bpermute_b32 v195, v151, v187
	s_waitcnt lgkmcnt(0)
	v_add_f32_e32 v180, v180, v188
	v_add_f32_e32 v181, v181, v189
	v_add_f32_e32 v182, v182, v190
	v_add_f32_e32 v183, v183, v191
	v_add_f32_e32 v184, v184, v192
	v_add_f32_e32 v185, v185, v193
	v_add_f32_e32 v186, v186, v194
	v_add_f32_e32 v187, v187, v195
	v_lshl_add_u64 v[140:141], s[18:19], 0, v[136:137]
	s_and_saveexec_b64 s[2:3], s[38:39]
	s_cbranch_execz .LBB0_177
	v_add_co_u32_e32 v196, vcc, 0xf700000, v140
	s_nop 1
	v_addc_co_u32_e32 v197, vcc, 0, v141, vcc
	global_store_dword v[196:197], v180, off
	v_add_co_u32_e32 v196, vcc, 0xf704000, v140
	s_nop 1
	v_addc_co_u32_e32 v197, vcc, 0, v141, vcc
	global_store_dword v[196:197], v181, off
	v_add_co_u32_e32 v196, vcc, 0xf708000, v140
	s_nop 1
	v_addc_co_u32_e32 v197, vcc, 0, v141, vcc
	global_store_dword v[196:197], v182, off
	v_add_co_u32_e32 v196, vcc, 0xf70c000, v140
	s_nop 1
	v_addc_co_u32_e32 v197, vcc, 0, v141, vcc
	global_store_dword v[196:197], v183, off
	v_add_co_u32_e32 v196, vcc, 0xf710000, v140
	s_nop 1
	v_addc_co_u32_e32 v197, vcc, 0, v141, vcc
	global_store_dword v[196:197], v184, off
	v_add_co_u32_e32 v196, vcc, 0xf714000, v140
	s_nop 1
	v_addc_co_u32_e32 v197, vcc, 0, v141, vcc
	global_store_dword v[196:197], v185, off
	v_add_co_u32_e32 v196, vcc, 0xf718000, v140
	s_nop 1
	v_addc_co_u32_e32 v197, vcc, 0, v141, vcc
	global_store_dword v[196:197], v186, off
	v_add_co_u32_e32 v196, vcc, 0xf71c000, v140
	s_nop 1
	v_addc_co_u32_e32 v197, vcc, 0, v141, vcc
	global_store_dword v[196:197], v187, off
	s_branch .LBB0_177
